# prologue grid sync as single-counter barrier (with per-wave vmcnt(0) before it); near-bias table reads paired as ds_read2_b32
# speedup vs baseline: 1.0010x; 1.0010x over previous
; __global__ void __launch_bounds__(NWAVES * 64, 2) trunk_fwd(Args args) {
;     ...
;     grid.sync();
.LBB0_24:
	s_waitcnt vmcnt(0)
	v_lshrrev_b32_e32 v1, 20, v0
	v_lshrrev_b32_e32 v0, 10, v0
	v_or_b32_e32 v0, v0, v1
	s_movk_i32 s0, 0x3ff
	v_and_or_b32 v0, v0, s0, v232
	v_cmp_eq_u32_e32 vcc, 0, v0
	s_barrier
	s_and_saveexec_b64 s[0:1], vcc
	s_cbranch_execz .LBB0_34
	buffer_wbl2 sc1
	s_waitcnt vmcnt(0)
	v_mov_b32_e32 v2, 0x4000
	v_mov_b32_e32 v3, 1
	global_atomic_add v2, v3, s[70:71]
.Lgb_spin:
	s_sleep 1
	global_load_dword v0, v2, s[70:71] sc1
	s_waitcnt vmcnt(0)
	v_readfirstlane_b32 s6, v0
	s_cmp_lt_u32 s6, s74
	s_cbranch_scc1 .Lgb_spin
	buffer_inv sc1
	s_waitcnt vmcnt(0)

; #define SBAR() __builtin_amdgcn_sched_barrier(0)
; template<int THRL> __device__ __forceinline__ void attn_unit(int b,int h,int qb,const AttnArgs&A,char*shm,bool setup){
;     ...
;   bf16x8 qr[4];
;   #pragma unroll
;   for(int d0=0;d0<4;++d0)qr[d0]=*reinterpret_cast<const bf16x8*>(&Qw[(long)r32*PITCH+d0*16+hi*8]);
;   DMA_K(0,0); DMA_V(0,0); DMA_K(1,SLOT16);
;   DMA_V(1,SLOT16); { const unsigned char*g_=imgS+((size_t)(NT>2?2:NT-1)<<15); const unsigned d_=(unsigned)__builtin_amdgcn_readfirstlane(NT>2?kdst+2*SLOT16:ddst); glds16s(g_,voff,d_); glds16s(g_+8192,voff,d_+8192); }
;   float mhat=0.f,l=0.f;
;   f32x16 o[4];
;   #pragma unroll
;   for(int d0=0;d0<4;++d0)o[d0]=f32x16{};
;   const int qpos=qw0+r32;
;   f32x16 p0,p1; u32x4 pw[4]; bf16x8 kf[8]; bf16x8 va[4],vb[4];
;   f32x16 cini;
;   #pragma unroll
;   for(int r=0;r<16;++r)cini[r]=cfar;
;   asm volatile("":"+v"(cini));
;     ...
;   WAIT_BAR(8);
;   KRD(kp0);
;   int ks_t=0,ks_n=SLOT16,vs_t=0,vs_nn=2*SLOT16;
;   for(int t=0;t<NT;++t){
;     WAIT_BAR(4);
;     const int kv0=t*KVBLK;
;     const bool act=(kv0<=qw0+QBLK-1);
;     const bool actn=(t+1<NT)&&(kv0+KVBLK<=qw0+QBLK-1);
;     const lds_cptr vp=vp0+vs_t;
;     const bool dk=(t+3<NT), dv=(t+2<NT);
;     const unsigned char*gk_=imgS+((size_t)(dk?t+3:NT-1)<<15); const unsigned char*gv_=imgS+((size_t)(dv?t+2:NT-1)<<15)+16384;
;     const unsigned kd_=(unsigned)__builtin_amdgcn_readfirstlane(dk?kdst+ks_t:ddst), vd_=(unsigned)__builtin_amdgcn_readfirstlane(dv?vdst+vs_nn:ddst);
;     if(act){
;       VRK(va,vp,0); VRK(vb,vp,1);
;       SBAR();
;       QKM(cini);
;     }
;     if(act){
;       const bool far=(qw0-(kv0+63)>=113);
;       if(!far){ const float*bt=biasT+mp*128; const int dq=qpos-kv0-4*hi;
;         #pragma unroll
;         for(int r=0;r<16;++r){ const int d=dq-((r&3)+8*(r>>2));
;           const int i0=d<0?0:(d>127?127:d);
;           const float b0=bt[i0];
;           const float n0=d>=0?0.f:-INFINITY;
;           p0[r]=(p0[r]+(b0-cfar))+n0; if((r&7)==7)asm volatile("":::"memory"); }
;         #pragma unroll
;         for(int r=0;r<16;++r){ const int d1=dq-32-((r&3)+8*(r>>2));
;           const int i1=d1<0?0:(d1>127?127:d1);
;           const float b1=bt[i1];
;           const float n1=d1>=0?0.f:-INFINITY;
;           p1[r]=(p1[r]+(b1-cfar))+n1; if((r&7)==7)asm volatile("":::"memory"); } }
.Lprio_skip:
	global_load_dwordx4 v[130:133], v0, s[8:9]
	global_load_dwordx4 v[134:137], v0, s[8:9] offset:32
	global_load_dwordx4 v[138:141], v0, s[8:9] offset:64
	global_load_dwordx4 v[142:145], v0, s[8:9] offset:96
	s_lshl_b32 s8, s47, 9
	s_add_i32 s29, s8, 0
	s_lshl_b32 s41, s20, 10
	s_add_i32 s29, s29, 0x18800
	s_cmp_lg_u32 0, -1
	s_cselect_b32 s8, 0, 0
	v_and_b32_e32 v207, 63, v2
	v_mov_b32_e32 v0, s29
	s_add_i32 s46, s41, s8
	s_add_i32 s8, s22, 0x80
	v_lshl_or_b32 v209, v207, 4, s41
	s_waitcnt vmcnt(19)
	ds_read_b32 v64, v0 offset:508
	s_ashr_i32 s72, s8, 6
	s_mov_b32 s8, m0
	s_mov_b32 m0, s46
	s_nop 0
	global_load_lds_dwordx4 v209, s[42:43]
	s_mov_b32 m0, s8
	s_add_i32 s8, s46, 0x2000
	s_mov_b32 s9, m0
	s_mov_b32 m0, s8
	s_nop 0
	global_load_lds_dwordx4 v209, s[30:31]
	s_mov_b32 m0, s9
	s_add_i32 s99, s46, 0xc000
	s_mov_b32 s8, m0
	s_mov_b32 m0, s99
	s_nop 0
	global_load_lds_dwordx4 v209, s[34:35]
	s_mov_b32 m0, s8
	s_add_i32 s8, s46, 0xe000
	s_mov_b32 s9, m0
	s_mov_b32 m0, s8
	s_nop 0
	global_load_lds_dwordx4 v209, s[92:93]
	s_mov_b32 m0, s9
	s_add_i32 s8, s46, 0x4000
	s_mov_b32 s9, m0
	s_mov_b32 m0, s8
	s_nop 0
	global_load_lds_dwordx4 v209, s[96:97]
	s_mov_b32 m0, s9
	s_add_i32 s8, s46, 0x6000
	s_mov_b32 s9, m0
	s_mov_b32 m0, s8
	s_nop 0
	global_load_lds_dwordx4 v209, s[4:5]
	s_mov_b32 m0, s9
	s_add_i32 s8, s46, 0x10000
	s_mov_b32 s9, m0
	s_mov_b32 m0, s8
	s_nop 0
	global_load_lds_dwordx4 v209, s[6:7]
	s_mov_b32 m0, s9
	s_add_i32 s8, s46, 0x12000
	s_add_i32 s81, s72, -1
	s_mov_b32 s9, m0
	s_mov_b32 m0, s8
	s_nop 0
	global_load_lds_dwordx4 v209, s[12:13]
	s_mov_b32 m0, s9
	s_min_i32 s8, s81, 2
	s_ashr_i32 s9, s8, 31
	s_add_i32 s98, s46, 0x19000
	s_lshl_b64 s[8:9], s[8:9], 15
	s_add_u32 s8, s42, s8
	s_addc_u32 s9, s43, s9
	s_add_i32 s20, s46, 0x8000
	s_cmp_gt_i32 s72, 2
	s_cselect_b64 vcc, -1, 0
	s_waitcnt lgkmcnt(0)
	v_mov_b32_e32 v78, v64
	v_mov_b32_e32 v79, v64
	s_and_b64 s[82:83], vcc, exec
	v_mov_b32_e32 v65, v64
	v_mov_b32_e32 v66, v64
	v_mov_b32_e32 v67, v64
	v_mov_b32_e32 v68, v64
	v_mov_b32_e32 v69, v64
	v_mov_b32_e32 v70, v64
	v_mov_b32_e32 v71, v64
	v_mov_b32_e32 v72, v64
	v_mov_b32_e32 v73, v64
	v_mov_b32_e32 v74, v64
	v_mov_b32_e32 v75, v64
	v_mov_b32_e32 v76, v64
	v_mov_b32_e32 v77, v64
	s_waitcnt vmcnt(9)
	v_mov_b64_e32 v[112:113], v[78:79]
	s_cselect_b32 s20, s20, s98
	s_mov_b32 s21, m0
	s_mov_b32 m0, s20
	s_nop 0
	global_load_lds_dwordx4 v209, s[8:9]
	s_mov_b32 m0, s21
	s_add_u32 s82, s8, 0x2000
	v_mov_b64_e32 v[110:111], v[76:77]
	v_mov_b64_e32 v[108:109], v[74:75]
	v_mov_b64_e32 v[106:107], v[72:73]
	v_mov_b64_e32 v[104:105], v[70:71]
	v_mov_b64_e32 v[102:103], v[68:69]
	v_mov_b64_e32 v[100:101], v[66:67]
	v_mov_b64_e32 v[98:99], v[64:65]
	s_addc_u32 s83, s9, 0
	s_addk_i32 s20, 0x2000
	s_mov_b32 s21, m0
	s_mov_b32 m0, s20
	s_nop 0
	global_load_lds_dwordx4 v209, s[82:83]
	s_mov_b32 m0, s21
	s_waitcnt vmcnt(8) lgkmcnt(0)
	s_barrier
	s_cmp_lt_i32 s72, 1
	s_cbranch_scc1 .LBB0_251
	s_lshl_b32 s20, s47, 13
	v_lshlrev_b32_e32 v0, 10, v206
	v_lshlrev_b32_e32 v2, 4, v208
	s_add_i32 s20, s20, 0
	v_add3_u32 v65, s20, v0, v2
	ds_read_b128 v[114:117], v65
	ds_read_b128 v[118:121], v65 offset:512
	ds_read_b128 v[122:125], v65 offset:2048
	ds_read_b128 v[126:129], v65 offset:2560
	ds_read_b128 v[146:149], v65 offset:4096
	ds_read_b128 v[150:153], v65 offset:4608
	ds_read_b128 v[154:157], v65 offset:6144
	ds_read_b128 v[158:161], v65 offset:6656
	s_cmp_gt_u32 s72, 3
	s_cselect_b32 s82, s46, s98
	s_cmp_lg_u32 0, -1
	s_cselect_b32 s20, 0, 0
	s_add_i32 s20, s20, s41
	s_waitcnt vmcnt(4) lgkmcnt(0)
	s_barrier
	s_add_i32 s20, s20, 0x14000
	v_lshlrev_b32_e32 v3, 9, v206
	s_and_b64 s[94:95], vcc, exec
	v_add3_u32 v210, 0, v3, v2
	v_lshlrev_b32_e32 v212, 2, v206
	s_cselect_b32 s73, s20, s98
	s_cmp_gt_i32 s22, -1
	s_mov_b64 vcc, -1
	s_cbranch_scc0 .LBB0_240
	ds_read_b128 v[42:45], v210 offset:49152
	ds_read_b128 v[174:177], v210 offset:50176
	ds_read_b128 v[38:41], v210 offset:53248
	ds_read_b128 v[170:173], v210 offset:54272
	ds_read_b128 v[34:37], v210 offset:57344
	ds_read_b128 v[166:169], v210 offset:58368
	ds_read_b128 v[178:181], v210 offset:61440
	ds_read_b128 v[162:165], v210 offset:62464
	s_sub_i32 s20, s40, 63
	s_waitcnt lgkmcnt(14)
	v_mfma_f32_32x32x16_bf16 v[18:33], v[114:117], v[130:133], v[98:113]
	s_cmpk_gt_i32 s20, 0x70
	v_mfma_f32_32x32x16_bf16 v[2:17], v[118:121], v[130:133], v[98:113]
	s_waitcnt lgkmcnt(12)
	v_mfma_f32_32x32x16_bf16 v[2:17], v[126:129], v[134:137], v[2:17]
	v_mfma_f32_32x32x16_bf16 v[18:33], v[122:125], v[134:137], v[18:33]
	s_waitcnt lgkmcnt(10)
	v_mfma_f32_32x32x16_bf16 v[2:17], v[150:153], v[138:141], v[2:17]
	v_mfma_f32_32x32x16_bf16 v[18:33], v[146:149], v[138:141], v[18:33]
	s_waitcnt lgkmcnt(8)
	v_mfma_f32_32x32x16_bf16 v[2:17], v[158:161], v[142:145], v[2:17]
	v_mfma_f32_32x32x16_bf16 v[18:33], v[154:157], v[142:145], v[18:33]
	s_cbranch_scc1 .LBB0_239
	v_or_b32_e32 v0, s40, v208
	v_sub_u32_e32 v0, v0, v212
	s_sub_i32 s20, s29, 0x18800
	s_lshl_b32 s20, s20, 1
	s_add_i32 s20, s20, 0x1d000
	v_lshl_add_u32 v82, v0, 2, s20
	ds_read2_b32 v[46:47], v82 offset0:63 offset1:62
	ds_read2_b32 v[48:49], v82 offset0:61 offset1:60
	ds_read2_b32 v[50:51], v82 offset0:55 offset1:54
	ds_read2_b32 v[52:53], v82 offset0:53 offset1:52
	ds_read2_b32 v[54:55], v82 offset0:47 offset1:46
	ds_read2_b32 v[56:57], v82 offset0:45 offset1:44
	ds_read2_b32 v[58:59], v82 offset0:39 offset1:38
	ds_read2_b32 v[60:61], v82 offset0:37 offset1:36
	ds_read2_b32 v[66:67], v82 offset0:31 offset1:30
	ds_read2_b32 v[68:69], v82 offset0:29 offset1:28
	ds_read2_b32 v[70:71], v82 offset0:23 offset1:22
	ds_read2_b32 v[72:73], v82 offset0:21 offset1:20
	ds_read2_b32 v[74:75], v82 offset0:15 offset1:14
	ds_read2_b32 v[76:77], v82 offset0:13 offset1:12
	ds_read2_b32 v[78:79], v82 offset0:7 offset1:6
	ds_read2_b32 v[80:81], v82 offset0:5 offset1:4
	s_waitcnt lgkmcnt(8)
	v_pk_add_f32 v[18:19], v[18:19], v[46:47]
	v_pk_add_f32 v[20:21], v[20:21], v[48:49]
	v_pk_add_f32 v[22:23], v[22:23], v[50:51]
	v_pk_add_f32 v[24:25], v[24:25], v[52:53]
	v_pk_add_f32 v[26:27], v[26:27], v[54:55]
	v_pk_add_f32 v[28:29], v[28:29], v[56:57]
	v_pk_add_f32 v[30:31], v[30:31], v[58:59]
	v_pk_add_f32 v[32:33], v[32:33], v[60:61]
	s_waitcnt lgkmcnt(0)
	v_pk_add_f32 v[2:3], v[2:3], v[66:67]
	v_pk_add_f32 v[4:5], v[4:5], v[68:69]
	v_pk_add_f32 v[6:7], v[6:7], v[70:71]
	v_pk_add_f32 v[8:9], v[8:9], v[72:73]
	v_pk_add_f32 v[10:11], v[10:11], v[74:75]
	v_pk_add_f32 v[12:13], v[12:13], v[76:77]
	v_pk_add_f32 v[14:15], v[14:15], v[78:79]
	v_pk_add_f32 v[16:17], v[16:17], v[80:81]

; #define SBAR() __builtin_amdgcn_sched_barrier(0)
; #define WAIT_BAR(N) asm volatile("s_waitcnt vmcnt(" #N ") lgkmcnt(0)\n\ts_barrier":::"memory")
;   #define VRK(dst,vp_,ks_) do{ _Pragma("unroll") for(int d0_=0;d0_<4;++d0_){ dst[d0_]=*(const __attribute__((address_space(3))) bf16x8*)((vp_)+d0_*4096+(ks_)*1024); } }while(0)
; template<int THRL> __device__ __forceinline__ void attn_unit(int b,int h,int qb,const AttnArgs&A,char*shm,bool setup){
;     ...
;     WAIT_BAR(4);
;     const int kv0=t*KVBLK;
;     const bool act=(kv0<=qw0+QBLK-1);
;     const bool actn=(t+1<NT)&&(kv0+KVBLK<=qw0+QBLK-1);
;     const lds_cptr vp=vp0+vs_t;
;     const bool dk=(t+3<NT), dv=(t+2<NT);
;     const unsigned char*gk_=imgS+((size_t)(dk?t+3:NT-1)<<15); const unsigned char*gv_=imgS+((size_t)(dv?t+2:NT-1)<<15)+16384;
;     const unsigned kd_=(unsigned)__builtin_amdgcn_readfirstlane(dk?kdst+ks_t:ddst), vd_=(unsigned)__builtin_amdgcn_readfirstlane(dv?vdst+vs_nn:ddst);
;     if(act){
;       VRK(va,vp,0); VRK(vb,vp,1);
;       SBAR();
;       QKM(cini);
;     }
;     if(act){
;       const bool far=(qw0-(kv0+63)>=113);
;       if(!far){ const float*bt=biasT+mp*128; const int dq=qpos-kv0-4*hi;
;         #pragma unroll
;         for(int r=0;r<16;++r){ const int d=dq-((r&3)+8*(r>>2));
;           const int i0=d<0?0:(d>127?127:d);
;           const float b0=bt[i0];
;           const float n0=d>=0?0.f:-INFINITY;
;           p0[r]=(p0[r]+(b0-cfar))+n0; if((r&7)==7)asm volatile("":::"memory"); }
;         #pragma unroll
;         for(int r=0;r<16;++r){ const int d1=dq-32-((r&3)+8*(r>>2));
;           const int i1=d1<0?0:(d1>127?127:d1);
;           const float b1=bt[i1];
;           const float n1=d1>=0?0.f:-INFINITY;
;           p1[r]=(p1[r]+(b1-cfar))+n1; if((r&7)==7)asm volatile("":::"memory"); } }
.LBB0_243:
	s_add_i32 s95, s41, 1
	s_add_i32 s20, s94, s46
	s_cmp_lt_i32 s41, s81
	s_cselect_b32 s82, s20, s98
	s_add_i32 s20, s9, s99
	s_waitcnt vmcnt(4) lgkmcnt(0)
	s_barrier
	s_cmp_lt_i32 s41, s72
	s_cselect_b32 s73, s20, s98
	s_cmp_lt_i32 s22, 0xffffffa2
	s_cbranch_scc1 .Ltr_inact
	v_add_u32_e32 v15, s94, v210
	ds_read_b128 v[162:165], v15 offset:49152
	ds_read_b128 v[146:149], v15 offset:50176
	ds_read_b128 v[158:161], v15 offset:53248
	ds_read_b128 v[10:13], v15 offset:54272
	ds_read_b128 v[154:157], v15 offset:57344
	ds_read_b128 v[6:9], v15 offset:58368
	ds_read_b128 v[150:153], v15 offset:61440
	ds_read_b128 v[2:5], v15 offset:62464
	v_mfma_f32_32x32x16_bf16 v[114:129], v[178:181], v[130:133], v[82:97]
	s_cmpk_gt_i32 s22, 0x70
	v_mfma_f32_32x32x16_bf16 v[98:113], v[182:185], v[130:133], v[82:97]
	v_mfma_f32_32x32x16_bf16 v[98:113], v[186:189], v[134:137], v[98:113]
	v_mfma_f32_32x32x16_bf16 v[114:129], v[166:169], v[134:137], v[114:129]
	v_mfma_f32_32x32x16_bf16 v[98:113], v[190:193], v[138:141], v[98:113]
	v_mfma_f32_32x32x16_bf16 v[114:129], v[174:177], v[138:141], v[114:129]
	v_mfma_f32_32x32x16_bf16 v[98:113], v[194:197], v[142:145], v[98:113]
	v_mfma_f32_32x32x16_bf16 v[114:129], v[170:173], v[142:145], v[114:129]
	s_cbranch_scc1 .LBB0_246
	v_lshlrev_b32_e32 v212, 2, v206
	v_sub_u32_e32 v212, v208, v212
	v_add_u32_e32 v212, s22, v212
	s_sub_i32 s20, s29, 0x18800
	s_lshl_b32 s20, s20, 1
	s_add_i32 s20, s20, 0x1d000
	v_lshl_add_u32 v213, v212, 2, s20
	ds_read2_b32 v[166:167], v213 offset0:126 offset1:125
	ds_read2_b32 v[168:169], v213 offset0:124 offset1:123
	ds_read2_b32 v[170:171], v213 offset0:118 offset1:117
	ds_read2_b32 v[172:173], v213 offset0:116 offset1:115
	ds_read2_b32 v[174:175], v213 offset0:110 offset1:109
	ds_read2_b32 v[176:177], v213 offset0:108 offset1:107
	ds_read2_b32 v[178:179], v213 offset0:102 offset1:101
	ds_read2_b32 v[180:181], v213 offset0:100 offset1:99
	ds_read2_b32 v[182:183], v213 offset0:94 offset1:93
	ds_read2_b32 v[184:185], v213 offset0:92 offset1:91
	ds_read2_b32 v[186:187], v213 offset0:86 offset1:85
	ds_read2_b32 v[188:189], v213 offset0:84 offset1:83
	ds_read2_b32 v[190:191], v213 offset0:78 offset1:77
	ds_read2_b32 v[192:193], v213 offset0:76 offset1:75
	ds_read2_b32 v[194:195], v213 offset0:70 offset1:69
	ds_read2_b32 v[196:197], v213 offset0:68 offset1:67
	s_waitcnt lgkmcnt(8)
	v_pk_add_f32 v[114:115], v[114:115], v[166:167]
	v_pk_add_f32 v[116:117], v[116:117], v[168:169]
	v_pk_add_f32 v[118:119], v[118:119], v[170:171]
	v_pk_add_f32 v[120:121], v[120:121], v[172:173]
	v_pk_add_f32 v[122:123], v[122:123], v[174:175]
	v_pk_add_f32 v[124:125], v[124:125], v[176:177]
	v_pk_add_f32 v[126:127], v[126:127], v[178:179]
	v_pk_add_f32 v[128:129], v[128:129], v[180:181]
	s_waitcnt lgkmcnt(0)
	v_pk_add_f32 v[98:99], v[98:99], v[182:183]
	v_pk_add_f32 v[100:101], v[100:101], v[184:185]
	v_pk_add_f32 v[102:103], v[102:103], v[186:187]
	v_pk_add_f32 v[104:105], v[104:105], v[188:189]
	v_pk_add_f32 v[106:107], v[106:107], v[190:191]
	v_pk_add_f32 v[108:109], v[108:109], v[192:193]
	v_pk_add_f32 v[110:111], v[110:111], v[194:195]
	v_pk_add_f32 v[112:113], v[112:113], v[196:197]
